# code placement: 4-byte phase of the hand-written retention loop flipped (s_nop 0 before the loop head and after the back edge)
# speedup vs baseline: 1.0030x; 1.0027x over previous
; __device__ __forceinline__ void ret_pair(LAS unsigned char* lds, const bf16_t* Z, bf16_t* MIX, int b, int h, int tA, int tB, const float* gain, int wid) {
;     ...
;     asm volatile("s_waitcnt lgkmcnt(0)\n\ts_barrier" ::: "memory");
;     RP_DMA(0, 0); RP_DMA(1, 1);
;     asm volatile("s_waitcnt vmcnt(3) lgkmcnt(0)\n\ts_barrier" ::: "memory");
;     ...
;     int bcur = 0;
;     for (int kt = 0; kt < nkt; ++kt) {
.Lrx_b0:
	s_barrier
	s_mov_b32 s98, 1
	s_nop 0

; __device__ __forceinline__ void ret_pair(LAS unsigned char* lds, const bf16_t* Z, bf16_t* MIX, int b, int h, int tA, int tB, const float* gain, int wid) {
;     ...
;         if (kt + 1 < nkt) { if (more2) asm volatile("s_waitcnt vmcnt(3) lgkmcnt(0)\n\ts_barrier" ::: "memory"); else asm volatile("s_waitcnt vmcnt(0) lgkmcnt(0)\n\ts_barrier" ::: "memory"); }
;         bcur = bnx;
.Lrx_bar:
	s_barrier
	s_branch .Lrx_loop
	s_nop 0
